# FNet stage-B wave item hand-written (all operand loads in flight at once)
# speedup vs baseline: 1.5370x; 1.0077x over previous
.LBB0_446:
	s_cmp_ge_i32 s12, s60
	s_cbranch_scc0 .LBB0_479
	s_cmp_ge_i32 s12, s61
	s_cbranch_scc0 .LBB0_449
	s_sub_i32 s6, s12, s61
	s_and_b32 s7, s6, 63
	s_bfe_u32 s8, s6, 0x20006
	s_lshr_b32 s9, s6, 8
	v_and_b32_e32 v180, 15, v205
	v_lshrrev_b32_e32 v181, 4, v205
	v_lshlrev_b32_e32 v182, 7, v180
	v_lshl_add_u32 v182, v181, 4, v182
	v_add_u32_e32 v184, 0x1000, v182
	s_lshl_b32 s10, s9, 2
	s_add_i32 s10, s10, s8
	s_lshl_b32 s10, s10, 6
	s_add_i32 s10, s10, s7
	s_lshl_b32 s10, s10, 14
	s_add_u32 s10, s10, 0xac00000
	s_add_u32 s16, s4, s10
	s_addc_u32 s17, s5, 0
	s_add_u32 s18, s4, 0x40000
	s_addc_u32 s19, s5, 0
	s_add_u32 s20, s4, 0x42000
	s_addc_u32 s21, s5, 0
	global_load_dwordx4 v[64:67], v182, s[18:19] offset:0
	global_load_dwordx4 v[96:99], v182, s[20:21] offset:0
	global_load_dwordx4 v[68:71], v182, s[18:19] offset:64
	global_load_dwordx4 v[100:103], v182, s[20:21] offset:64
	global_load_dwordx4 v[72:75], v182, s[18:19] offset:2048
	global_load_dwordx4 v[104:107], v182, s[20:21] offset:2048
	global_load_dwordx4 v[76:79], v182, s[18:19] offset:2112
	global_load_dwordx4 v[108:111], v182, s[20:21] offset:2112
	global_load_dwordx4 v[80:83], v184, s[18:19] offset:0
	global_load_dwordx4 v[112:115], v184, s[20:21] offset:0
	global_load_dwordx4 v[84:87], v184, s[18:19] offset:64
	global_load_dwordx4 v[116:119], v184, s[20:21] offset:64
	global_load_dwordx4 v[88:91], v184, s[18:19] offset:2048
	global_load_dwordx4 v[120:123], v184, s[20:21] offset:2048
	global_load_dwordx4 v[92:95], v184, s[18:19] offset:2112
	global_load_dwordx4 v[124:127], v184, s[20:21] offset:2112
	global_load_dwordx4 v[138:141], v182, s[16:17] offset:0
	global_load_dwordx4 v[142:145], v182, s[16:17] offset:64
	global_load_dwordx4 v[146:149], v182, s[16:17] offset:2048
	global_load_dwordx4 v[150:153], v182, s[16:17] offset:2112
	global_load_dwordx4 v[154:157], v184, s[16:17] offset:0
	global_load_dwordx4 v[158:161], v184, s[16:17] offset:64
	global_load_dwordx4 v[162:165], v184, s[16:17] offset:2048
	global_load_dwordx4 v[166:169], v184, s[16:17] offset:2112
	s_add_u32 s22, s16, 0x2000
	s_addc_u32 s23, s17, 0
	global_load_dwordx4 v[170:173], v182, s[22:23] offset:0
	global_load_dwordx4 v[174:177], v182, s[22:23] offset:64
	global_load_dwordx4 v[128:131], v182, s[22:23] offset:2048
	global_load_dwordx4 v[132:135], v182, s[22:23] offset:2112
	s_lshl_b32 s10, s9, 12
	s_add_i32 s10, s10, s7
	s_addk_i32 s10, 0x400
	s_lshl_b32 s10, s10, 9
	s_lshl_b32 s11, s8, 7
	s_add_i32 s10, s10, s11
	s_add_u32 s10, s10, 0xbc00000
	s_add_u32 s10, s4, s10
	s_addc_u32 s11, s5, 0
	v_lshlrev_b32_e32 v183, 15, v180
	v_lshl_add_u32 v183, v181, 3, v183
	s_waitcnt vmcnt(12)
	v_xor_b32_e32 v96, 0x80008000, v96
	v_xor_b32_e32 v97, 0x80008000, v97
	v_xor_b32_e32 v98, 0x80008000, v98
	v_xor_b32_e32 v99, 0x80008000, v99
	v_xor_b32_e32 v100, 0x80008000, v100
	v_xor_b32_e32 v101, 0x80008000, v101
	v_xor_b32_e32 v102, 0x80008000, v102
	v_xor_b32_e32 v103, 0x80008000, v103
	v_xor_b32_e32 v104, 0x80008000, v104
	v_xor_b32_e32 v105, 0x80008000, v105
	v_xor_b32_e32 v106, 0x80008000, v106
	v_xor_b32_e32 v107, 0x80008000, v107
	v_xor_b32_e32 v108, 0x80008000, v108
	v_xor_b32_e32 v109, 0x80008000, v109
	v_xor_b32_e32 v110, 0x80008000, v110
	v_xor_b32_e32 v111, 0x80008000, v111
	v_xor_b32_e32 v112, 0x80008000, v112
	v_xor_b32_e32 v113, 0x80008000, v113
	v_xor_b32_e32 v114, 0x80008000, v114
	v_xor_b32_e32 v115, 0x80008000, v115
	v_xor_b32_e32 v116, 0x80008000, v116
	v_xor_b32_e32 v117, 0x80008000, v117
	v_xor_b32_e32 v118, 0x80008000, v118
	v_xor_b32_e32 v119, 0x80008000, v119
	v_xor_b32_e32 v120, 0x80008000, v120
	v_xor_b32_e32 v121, 0x80008000, v121
	v_xor_b32_e32 v122, 0x80008000, v122
	v_xor_b32_e32 v123, 0x80008000, v123
	v_xor_b32_e32 v124, 0x80008000, v124
	v_xor_b32_e32 v125, 0x80008000, v125
	v_xor_b32_e32 v126, 0x80008000, v126
	v_xor_b32_e32 v127, 0x80008000, v127
	s_waitcnt vmcnt(11)
	v_mfma_f32_16x16x32_bf16 v[0:3], v[138:141], v[64:67], 0
	v_mfma_f32_16x16x32_bf16 v[4:7], v[138:141], v[72:75], 0
	v_mfma_f32_16x16x32_bf16 v[8:11], v[138:141], v[80:83], 0
	v_mfma_f32_16x16x32_bf16 v[12:15], v[138:141], v[88:91], 0
	s_waitcnt vmcnt(10)
	v_mfma_f32_16x16x32_bf16 v[0:3], v[142:145], v[68:71], v[0:3]
	v_mfma_f32_16x16x32_bf16 v[4:7], v[142:145], v[76:79], v[4:7]
	v_mfma_f32_16x16x32_bf16 v[8:11], v[142:145], v[84:87], v[8:11]
	v_mfma_f32_16x16x32_bf16 v[12:15], v[142:145], v[92:95], v[12:15]
	s_waitcnt vmcnt(3)
	v_mfma_f32_16x16x32_bf16 v[0:3], v[170:173], v[96:99], v[0:3]
	v_mfma_f32_16x16x32_bf16 v[4:7], v[170:173], v[104:107], v[4:7]
	v_mfma_f32_16x16x32_bf16 v[8:11], v[170:173], v[112:115], v[8:11]
	v_mfma_f32_16x16x32_bf16 v[12:15], v[170:173], v[120:123], v[12:15]
	s_waitcnt vmcnt(2)
	v_mfma_f32_16x16x32_bf16 v[0:3], v[174:177], v[100:103], v[0:3]
	v_mfma_f32_16x16x32_bf16 v[4:7], v[174:177], v[108:111], v[4:7]
	v_mfma_f32_16x16x32_bf16 v[8:11], v[174:177], v[116:119], v[8:11]
	v_mfma_f32_16x16x32_bf16 v[12:15], v[174:177], v[124:127], v[12:15]
	global_load_dwordx4 v[170:173], v184, s[22:23] offset:0
	global_load_dwordx4 v[174:177], v184, s[22:23] offset:64
	v_mfma_f32_16x16x32_bf16 v[16:19], v[146:149], v[64:67], 0
	v_mfma_f32_16x16x32_bf16 v[20:23], v[146:149], v[72:75], 0
	v_mfma_f32_16x16x32_bf16 v[24:27], v[146:149], v[80:83], 0
	v_mfma_f32_16x16x32_bf16 v[28:31], v[146:149], v[88:91], 0
	v_mfma_f32_16x16x32_bf16 v[16:19], v[150:153], v[68:71], v[16:19]
	v_mfma_f32_16x16x32_bf16 v[20:23], v[150:153], v[76:79], v[20:23]
	v_mfma_f32_16x16x32_bf16 v[24:27], v[150:153], v[84:87], v[24:27]
	v_mfma_f32_16x16x32_bf16 v[28:31], v[150:153], v[92:95], v[28:31]
	s_waitcnt vmcnt(3)
	v_mfma_f32_16x16x32_bf16 v[16:19], v[128:131], v[96:99], v[16:19]
	v_mfma_f32_16x16x32_bf16 v[20:23], v[128:131], v[104:107], v[20:23]
	v_mfma_f32_16x16x32_bf16 v[24:27], v[128:131], v[112:115], v[24:27]
	v_mfma_f32_16x16x32_bf16 v[28:31], v[128:131], v[120:123], v[28:31]
	s_waitcnt vmcnt(2)
	v_mfma_f32_16x16x32_bf16 v[16:19], v[132:135], v[100:103], v[16:19]
	v_mfma_f32_16x16x32_bf16 v[20:23], v[132:135], v[108:111], v[20:23]
	v_mfma_f32_16x16x32_bf16 v[24:27], v[132:135], v[116:119], v[24:27]
	v_mfma_f32_16x16x32_bf16 v[28:31], v[132:135], v[124:127], v[28:31]
	global_load_dwordx4 v[128:131], v184, s[22:23] offset:2048
	global_load_dwordx4 v[132:135], v184, s[22:23] offset:2112
	v_mfma_f32_16x16x32_bf16 v[32:35], v[154:157], v[64:67], 0
	v_mfma_f32_16x16x32_bf16 v[36:39], v[154:157], v[72:75], 0
	v_mfma_f32_16x16x32_bf16 v[40:43], v[154:157], v[80:83], 0
	v_mfma_f32_16x16x32_bf16 v[44:47], v[154:157], v[88:91], 0
	v_mfma_f32_16x16x32_bf16 v[32:35], v[158:161], v[68:71], v[32:35]
	v_mfma_f32_16x16x32_bf16 v[36:39], v[158:161], v[76:79], v[36:39]
	v_mfma_f32_16x16x32_bf16 v[40:43], v[158:161], v[84:87], v[40:43]
	v_mfma_f32_16x16x32_bf16 v[44:47], v[158:161], v[92:95], v[44:47]
	s_waitcnt vmcnt(3)
	v_mfma_f32_16x16x32_bf16 v[32:35], v[170:173], v[96:99], v[32:35]
	v_mfma_f32_16x16x32_bf16 v[36:39], v[170:173], v[104:107], v[36:39]
	v_mfma_f32_16x16x32_bf16 v[40:43], v[170:173], v[112:115], v[40:43]
	v_mfma_f32_16x16x32_bf16 v[44:47], v[170:173], v[120:123], v[44:47]
	s_waitcnt vmcnt(2)
	v_mfma_f32_16x16x32_bf16 v[32:35], v[174:177], v[100:103], v[32:35]
	v_mfma_f32_16x16x32_bf16 v[36:39], v[174:177], v[108:111], v[36:39]
	v_mfma_f32_16x16x32_bf16 v[40:43], v[174:177], v[116:119], v[40:43]
	v_mfma_f32_16x16x32_bf16 v[44:47], v[174:177], v[124:127], v[44:47]
	v_mfma_f32_16x16x32_bf16 v[48:51], v[162:165], v[64:67], 0
	v_mfma_f32_16x16x32_bf16 v[52:55], v[162:165], v[72:75], 0
	v_mfma_f32_16x16x32_bf16 v[56:59], v[162:165], v[80:83], 0
	v_mfma_f32_16x16x32_bf16 v[60:63], v[162:165], v[88:91], 0
	v_mfma_f32_16x16x32_bf16 v[48:51], v[166:169], v[68:71], v[48:51]
	v_mfma_f32_16x16x32_bf16 v[52:55], v[166:169], v[76:79], v[52:55]
	v_mfma_f32_16x16x32_bf16 v[56:59], v[166:169], v[84:87], v[56:59]
	v_mfma_f32_16x16x32_bf16 v[60:63], v[166:169], v[92:95], v[60:63]
	s_waitcnt vmcnt(1)
	v_mfma_f32_16x16x32_bf16 v[48:51], v[128:131], v[96:99], v[48:51]
	v_mfma_f32_16x16x32_bf16 v[52:55], v[128:131], v[104:107], v[52:55]
	v_mfma_f32_16x16x32_bf16 v[56:59], v[128:131], v[112:115], v[56:59]
	v_mfma_f32_16x16x32_bf16 v[60:63], v[128:131], v[120:123], v[60:63]
	s_waitcnt vmcnt(0)
	v_mfma_f32_16x16x32_bf16 v[48:51], v[132:135], v[100:103], v[48:51]
	v_mfma_f32_16x16x32_bf16 v[52:55], v[132:135], v[108:111], v[52:55]
	v_mfma_f32_16x16x32_bf16 v[56:59], v[132:135], v[116:119], v[56:59]
	v_mfma_f32_16x16x32_bf16 v[60:63], v[132:135], v[124:127], v[60:63]
	s_nop 7
	v_mul_f32_e32 v0, 0x3b000000, v0
	v_mul_f32_e32 v1, 0x3b000000, v1
	v_mul_f32_e32 v2, 0x3b000000, v2
	v_mul_f32_e32 v3, 0x3b000000, v3
	v_cvt_pk_bf16_f32 v0, v0, v1
	v_cvt_pk_bf16_f32 v1, v2, v3
	v_mul_f32_e32 v4, 0x3b000000, v4
	v_mul_f32_e32 v5, 0x3b000000, v5
	v_mul_f32_e32 v6, 0x3b000000, v6
	v_mul_f32_e32 v7, 0x3b000000, v7
	v_cvt_pk_bf16_f32 v4, v4, v5
	v_cvt_pk_bf16_f32 v5, v6, v7
	v_mul_f32_e32 v8, 0x3b000000, v8
	v_mul_f32_e32 v9, 0x3b000000, v9
	v_mul_f32_e32 v10, 0x3b000000, v10
	v_mul_f32_e32 v11, 0x3b000000, v11
	v_cvt_pk_bf16_f32 v8, v8, v9
	v_cvt_pk_bf16_f32 v9, v10, v11
	v_mul_f32_e32 v12, 0x3b000000, v12
	v_mul_f32_e32 v13, 0x3b000000, v13
	v_mul_f32_e32 v14, 0x3b000000, v14
	v_mul_f32_e32 v15, 0x3b000000, v15
	v_cvt_pk_bf16_f32 v12, v12, v13
	v_cvt_pk_bf16_f32 v13, v14, v15
	v_mul_f32_e32 v16, 0x3b000000, v16
	v_mul_f32_e32 v17, 0x3b000000, v17
	v_mul_f32_e32 v18, 0x3b000000, v18
	v_mul_f32_e32 v19, 0x3b000000, v19
	v_cvt_pk_bf16_f32 v16, v16, v17
	v_cvt_pk_bf16_f32 v17, v18, v19
	v_mul_f32_e32 v20, 0x3b000000, v20
	v_mul_f32_e32 v21, 0x3b000000, v21
	v_mul_f32_e32 v22, 0x3b000000, v22
	v_mul_f32_e32 v23, 0x3b000000, v23
	v_cvt_pk_bf16_f32 v20, v20, v21
	v_cvt_pk_bf16_f32 v21, v22, v23
	v_mul_f32_e32 v24, 0x3b000000, v24
	v_mul_f32_e32 v25, 0x3b000000, v25
	v_mul_f32_e32 v26, 0x3b000000, v26
	v_mul_f32_e32 v27, 0x3b000000, v27
	v_cvt_pk_bf16_f32 v24, v24, v25
	v_cvt_pk_bf16_f32 v25, v26, v27
	v_mul_f32_e32 v28, 0x3b000000, v28
	v_mul_f32_e32 v29, 0x3b000000, v29
	v_mul_f32_e32 v30, 0x3b000000, v30
	v_mul_f32_e32 v31, 0x3b000000, v31
	v_cvt_pk_bf16_f32 v28, v28, v29
	v_cvt_pk_bf16_f32 v29, v30, v31
	v_mul_f32_e32 v32, 0x3b000000, v32
	v_mul_f32_e32 v33, 0x3b000000, v33
	v_mul_f32_e32 v34, 0x3b000000, v34
	v_mul_f32_e32 v35, 0x3b000000, v35
	v_cvt_pk_bf16_f32 v32, v32, v33
	v_cvt_pk_bf16_f32 v33, v34, v35
	v_mul_f32_e32 v36, 0x3b000000, v36
	v_mul_f32_e32 v37, 0x3b000000, v37
	v_mul_f32_e32 v38, 0x3b000000, v38
	v_mul_f32_e32 v39, 0x3b000000, v39
	v_cvt_pk_bf16_f32 v36, v36, v37
	v_cvt_pk_bf16_f32 v37, v38, v39
	v_mul_f32_e32 v40, 0x3b000000, v40
	v_mul_f32_e32 v41, 0x3b000000, v41
	v_mul_f32_e32 v42, 0x3b000000, v42
	v_mul_f32_e32 v43, 0x3b000000, v43
	v_cvt_pk_bf16_f32 v40, v40, v41
	v_cvt_pk_bf16_f32 v41, v42, v43
	v_mul_f32_e32 v44, 0x3b000000, v44
	v_mul_f32_e32 v45, 0x3b000000, v45
	v_mul_f32_e32 v46, 0x3b000000, v46
	v_mul_f32_e32 v47, 0x3b000000, v47
	v_cvt_pk_bf16_f32 v44, v44, v45
	v_cvt_pk_bf16_f32 v45, v46, v47
	v_mul_f32_e32 v48, 0x3b000000, v48
	v_mul_f32_e32 v49, 0x3b000000, v49
	v_mul_f32_e32 v50, 0x3b000000, v50
	v_mul_f32_e32 v51, 0x3b000000, v51
	v_cvt_pk_bf16_f32 v48, v48, v49
	v_cvt_pk_bf16_f32 v49, v50, v51
	v_mul_f32_e32 v52, 0x3b000000, v52
	v_mul_f32_e32 v53, 0x3b000000, v53
	v_mul_f32_e32 v54, 0x3b000000, v54
	v_mul_f32_e32 v55, 0x3b000000, v55
	v_cvt_pk_bf16_f32 v52, v52, v53
	v_cvt_pk_bf16_f32 v53, v54, v55
	v_mul_f32_e32 v56, 0x3b000000, v56
	v_mul_f32_e32 v57, 0x3b000000, v57
	v_mul_f32_e32 v58, 0x3b000000, v58
	v_mul_f32_e32 v59, 0x3b000000, v59
	v_cvt_pk_bf16_f32 v56, v56, v57
	v_cvt_pk_bf16_f32 v57, v58, v59
	v_mul_f32_e32 v60, 0x3b000000, v60
	v_mul_f32_e32 v61, 0x3b000000, v61
	v_mul_f32_e32 v62, 0x3b000000, v62
	v_mul_f32_e32 v63, 0x3b000000, v63
	v_cvt_pk_bf16_f32 v60, v60, v61
	v_cvt_pk_bf16_f32 v61, v62, v63
	global_store_dwordx2 v183, v[0:1], s[10:11] offset:0
	global_store_dwordx2 v183, v[16:17], s[10:11] offset:32
	global_store_dwordx2 v183, v[32:33], s[10:11] offset:64
	global_store_dwordx2 v183, v[48:49], s[10:11] offset:96
	s_add_u32 s10, s10, 0x80000
	s_addc_u32 s11, s11, 0
	global_store_dwordx2 v183, v[4:5], s[10:11] offset:0
	global_store_dwordx2 v183, v[20:21], s[10:11] offset:32
	global_store_dwordx2 v183, v[36:37], s[10:11] offset:64
	global_store_dwordx2 v183, v[52:53], s[10:11] offset:96
	s_add_u32 s10, s10, 0x80000
	s_addc_u32 s11, s11, 0
	global_store_dwordx2 v183, v[8:9], s[10:11] offset:0
	global_store_dwordx2 v183, v[24:25], s[10:11] offset:32
	global_store_dwordx2 v183, v[40:41], s[10:11] offset:64
	global_store_dwordx2 v183, v[56:57], s[10:11] offset:96
	s_add_u32 s10, s10, 0x80000
	s_addc_u32 s11, s11, 0
	global_store_dwordx2 v183, v[12:13], s[10:11] offset:0
	global_store_dwordx2 v183, v[28:29], s[10:11] offset:32
	global_store_dwordx2 v183, v[44:45], s[10:11] offset:64
	global_store_dwordx2 v183, v[60:61], s[10:11] offset:96
	s_mov_b64 s[0:1], 0
